# dn_local_item: conv first-output taps and wave-0 gate loads issued together (was dependent round trips)
# speedup vs baseline: 1.0852x; 1.0012x over previous
.LBB0_505:
	s_mul_hi_i32 s2, s10, 0xfe03f81
	s_lshr_b32 s3, s2, 31
	s_ashr_i32 s2, s2, 4
	s_add_i32 s2, s2, s3
	s_mul_i32 s3, s2, 0x102
	s_sub_i32 s4, s10, s3
	s_ashr_i32 s3, s2, 2
	s_ashr_i32 s5, s4, 31
	s_and_b32 s11, s2, 3
	s_mul_hi_i32 s6, s3, 0x4080
	s_mul_i32 s7, s3, 0x4080
	s_lshl_b64 s[2:3], s[4:5], 6
	v_mov_b32_e32 v16, v160
	s_add_u32 s2, s7, s2
	s_movk_i32 s5, 0x180
	s_addc_u32 s3, s6, s3
	v_cmp_gt_i32_e32 vcc, s5, v16
	s_and_saveexec_b64 s[6:7], vcc
	s_cbranch_execz .LBB0_511
	s_mov_b32 s5, 0x2aaaaaab
	v_mul_hi_i32 v8, v16, s5
	v_lshrrev_b32_e32 v9, 31, v8
	v_ashrrev_i32_e32 v8, 5, v8
	v_add_u32_e32 v17, v8, v9
	s_movk_i32 s5, 0xc0
	v_mul_lo_u32 v8, v17, s5
	v_sub_u32_e32 v8, v16, v8
	v_ashrrev_i32_e32 v10, 6, v8
	v_cmp_eq_u32_e32 vcc, 1, v10
	v_mov_b32_e32 v11, 0x8200
	v_mov_b32_e32 v12, 0x4100
	v_cndmask_b32_e32 v11, v11, v12, vcc
	v_add_u32_e32 v11, 0x100, v11
	v_cmp_gt_u32_e32 vcc, 64, v8
	v_lshlrev_b32_e32 v12, 5, v17
	v_and_b32_e32 v9, 63, v8
	v_cndmask_b32_e32 v8, v11, v195, vcc
	v_lshl_add_u32 v18, s4, 6, v12
	v_lshl_add_u32 v14, v9, 2, v8
	v_or_b32_e32 v8, 31, v18
	s_movk_i32 s5, 0x6f
	v_cmp_lt_i32_e32 vcc, s5, v8
	s_movk_i32 s5, 0x2080
	v_mul_lo_u32 v15, v17, s5
	s_and_saveexec_b64 s[8:9], vcc
	s_xor_b64 s[8:9], exec, s[8:9]
	s_cbranch_execz .LBB0_508
	v_lshlrev_b32_e32 v8, 8, v10
	s_lshl_b32 s5, s11, 6
	v_or3_b32 v20, v8, s5, v9
	v_ashrrev_i32_e32 v21, 31, v20
	v_lshl_add_u64 v[22:23], v[20:21], 2, v[4:5]
	v_add_co_u32_e32 v8, vcc, 0x2000, v22
	v_ashrrev_i32_e32 v13, 31, v12
	s_nop 0
	v_addc_co_u32_e32 v9, vcc, 0, v23, vcc
	v_add_co_u32_e32 v10, vcc, 0x1000, v22
	v_lshl_add_u64 v[12:13], s[2:3], 0, v[12:13]
	s_nop 0
	v_addc_co_u32_e32 v11, vcc, 0, v23, vcc
	global_load_dword v9, v[8:9], off offset:1024
	s_nop 0
	global_load_dword v8, v[10:11], off offset:2048
	s_nop 0
	global_load_dword v11, v[22:23], off offset:3072
	global_load_dword v10, v[22:23], off
	v_mad_u64_u32 v[22:23], s[12:13], v12, s97, v[48:49]
	v_mov_b32_e32 v12, v23
	v_mad_u64_u32 v[12:13], s[12:13], v13, s97, v[12:13]
	v_mov_b32_e32 v23, v12
	v_lshl_add_u64 v[12:13], v[20:21], 1, v[22:23]
	s_movk_i32 s5, 0xd000
	v_add_co_u32_e32 v20, vcc, s5, v12
	s_movk_i32 s5, 0xf000
	s_nop 0
	v_addc_co_u32_e32 v21, vcc, -1, v13, vcc
	global_load_ushort v15, v[20:21], off
	v_add_co_u32_e32 v20, vcc, s5, v12
	s_movk_i32 s12, 0x6f
	s_nop 0
	v_addc_co_u32_e32 v21, vcc, -1, v13, vcc
	global_load_ushort v19, v[20:21], off offset:-3584
	global_load_ushort v65, v[12:13], off offset:-3072
	global_load_ushort v66, v[12:13], off offset:1536
	v_cmp_lt_u32_e32 vcc, s12, v18
	s_movk_i32 s5, 0x2080
	s_waitcnt vmcnt(3)
	v_lshlrev_b32_e32 v15, 16, v15
	v_cndmask_b32_e64 v20, 0, 1.0, vcc
	s_waitcnt vmcnt(2)
	v_lshlrev_b32_e32 v47, 16, v19
	v_mul_f32_e32 v19, v11, v47
	v_fmac_f32_e32 v19, v10, v15
	s_waitcnt vmcnt(1)
	v_lshlrev_b32_e32 v40, 16, v65
	v_fmac_f32_e32 v19, v8, v40
	s_waitcnt vmcnt(0)
	v_lshlrev_b32_e32 v37, 16, v66
	v_fmac_f32_e32 v19, v9, v37
	v_mul_f32_e32 v15, 0xbfb8aa3b, v19
	v_exp_f32_e32 v15, v15
	s_nop 0
	v_add_f32_e32 v15, 1.0, v15
	v_rcp_f32_e32 v15, v15
	s_nop 0
	v_mul_f32_e32 v15, v19, v15
	v_mul_f32_e32 v44, v20, v15
	v_mul_lo_u32 v15, v17, s5
	s_movk_i32 s5, 0x1000
	v_add_co_u32_e32 v22, vcc, s5, v12
	s_movk_i32 s5, 0x2000
	s_nop 0
	v_addc_co_u32_e32 v23, vcc, 0, v13, vcc
	global_load_ushort v64, v[22:23], off offset:2048
	v_add_co_u32_e32 v22, vcc, s5, v12
	s_movk_i32 s5, 0x3000
	s_nop 0
	v_addc_co_u32_e32 v23, vcc, 0, v13, vcc
	global_load_ushort v61, v[22:23], off offset:2560
	v_add_co_u32_e32 v22, vcc, s5, v12
	s_movk_i32 s5, 0x4000
	s_nop 0
	v_addc_co_u32_e32 v23, vcc, 0, v13, vcc
	global_load_ushort v59, v[22:23], off offset:3072
	v_add_co_u32_e32 v22, vcc, s5, v12
	s_movk_i32 s5, 0x6000
	s_nop 0
	v_addc_co_u32_e32 v23, vcc, 0, v13, vcc
	global_load_ushort v58, v[22:23], off offset:3584
	v_add_co_u32_e32 v22, vcc, s5, v12
	s_movk_i32 s5, 0x7000
	s_nop 0
	v_addc_co_u32_e32 v23, vcc, 0, v13, vcc
	global_load_ushort v57, v[22:23], off
	v_add_co_u32_e32 v22, vcc, s5, v12
	s_mov_b32 s5, 0x8000
	s_nop 0
	v_addc_co_u32_e32 v23, vcc, 0, v13, vcc
	global_load_ushort v56, v[22:23], off offset:512
	v_add_co_u32_e32 v22, vcc, s5, v12
	s_mov_b32 s5, 0x9000
	s_nop 0
	v_addc_co_u32_e32 v23, vcc, 0, v13, vcc
	global_load_ushort v43, v[22:23], off offset:1024
	v_add_co_u32_e32 v22, vcc, s5, v12
	s_mov_b32 s5, 0xa000
	s_nop 0
	v_addc_co_u32_e32 v23, vcc, 0, v13, vcc
	global_load_ushort v39, v[22:23], off offset:1536
	v_add_co_u32_e32 v22, vcc, s5, v12
	s_mov_b32 s5, 0xb000
	s_nop 0
	v_addc_co_u32_e32 v23, vcc, 0, v13, vcc
	global_load_ushort v45, v[22:23], off offset:2048
	v_add_co_u32_e32 v22, vcc, s5, v12
	s_mov_b32 s5, 0xc000
	s_nop 0
	v_addc_co_u32_e32 v23, vcc, 0, v13, vcc
	global_load_ushort v46, v[22:23], off offset:2560
	v_add_co_u32_e32 v22, vcc, s5, v12
	s_mov_b32 s5, 0xd000
	s_nop 0
	v_addc_co_u32_e32 v23, vcc, 0, v13, vcc
	global_load_ushort v42, v[22:23], off offset:3072
	v_add_co_u32_e32 v22, vcc, s5, v12
	s_mov_b32 s5, 0xf000
	s_nop 0
	v_addc_co_u32_e32 v23, vcc, 0, v13, vcc
	global_load_ushort v41, v[22:23], off offset:3584
	v_add_co_u32_e32 v22, vcc, s5, v12
	s_mov_b32 s5, 0x11000
	s_nop 0
	v_addc_co_u32_e32 v23, vcc, 0, v13, vcc
	global_load_ushort v38, v[22:23], off
	v_add_co_u32_e32 v22, vcc, s33, v12
	v_add_u32_e32 v17, v14, v15
	s_nop 0
	v_addc_co_u32_e32 v23, vcc, 0, v13, vcc
	global_load_ushort v36, v[22:23], off offset:512
	v_add_co_u32_e32 v22, vcc, s5, v12
	s_mov_b32 s5, 0x12000
	s_nop 0
	v_addc_co_u32_e32 v23, vcc, 0, v13, vcc
	global_load_ushort v35, v[22:23], off offset:1024
	v_add_co_u32_e32 v22, vcc, s5, v12
	s_mov_b32 s5, 0x13000
	s_nop 0
	v_addc_co_u32_e32 v23, vcc, 0, v13, vcc
	global_load_ushort v34, v[22:23], off offset:1536
	v_add_co_u32_e32 v22, vcc, s5, v12
	s_mov_b32 s5, 0x15000
	s_nop 0
	v_addc_co_u32_e32 v23, vcc, 0, v13, vcc
	global_load_ushort v33, v[22:23], off offset:2048
	v_add_co_u32_e32 v22, vcc, s92, v12
	s_waitcnt vmcnt(10)
	v_lshlrev_b32_e32 v43, 16, v43
	v_addc_co_u32_e32 v23, vcc, 0, v13, vcc
	global_load_ushort v32, v[22:23], off offset:2560
	v_add_co_u32_e32 v22, vcc, s5, v12
	s_mov_b32 s5, 0x16000
	s_nop 0
	v_addc_co_u32_e32 v23, vcc, 0, v13, vcc
	global_load_ushort v31, v[22:23], off offset:3072
	v_add_co_u32_e32 v22, vcc, s5, v12
	s_mov_b32 s5, 0x19000
	s_nop 0
	v_addc_co_u32_e32 v23, vcc, 0, v13, vcc
	global_load_ushort v30, v[22:23], off offset:3584
	v_add_co_u32_e32 v22, vcc, s93, v12
	s_waitcnt vmcnt(12)
	v_lshlrev_b32_e32 v39, 16, v39
	v_addc_co_u32_e32 v23, vcc, 0, v13, vcc
	global_load_ushort v29, v[22:23], off
	v_add_co_u32_e32 v22, vcc, s5, v12
	s_mov_b32 s5, 0x1a000
	s_nop 0
	v_addc_co_u32_e32 v23, vcc, 0, v13, vcc
	global_load_ushort v28, v[22:23], off offset:512
	v_add_co_u32_e32 v22, vcc, s5, v12
	s_mov_b32 s5, 0x1b000
	s_nop 0
	v_addc_co_u32_e32 v23, vcc, 0, v13, vcc
	global_load_ushort v27, v[22:23], off offset:1024
	v_add_co_u32_e32 v22, vcc, s5, v12
	s_mov_b32 s5, 0x1d000
	s_nop 0
	v_addc_co_u32_e32 v23, vcc, 0, v13, vcc
	global_load_ushort v26, v[22:23], off offset:1536
	v_add_co_u32_e32 v22, vcc, s82, v12
	s_waitcnt vmcnt(11)
	v_lshlrev_b32_e32 v38, 16, v38
	v_addc_co_u32_e32 v23, vcc, 0, v13, vcc
	global_load_ushort v25, v[22:23], off offset:2048
	v_add_co_u32_e32 v22, vcc, s5, v12
	s_mov_b32 s5, 0x1e000
	s_nop 0
	v_addc_co_u32_e32 v23, vcc, 0, v13, vcc
	global_load_ushort v24, v[22:23], off offset:2560
	v_add_co_u32_e32 v22, vcc, s5, v12
	s_mov_b32 s5, 0x1f000
	s_nop 0
	v_addc_co_u32_e32 v23, vcc, 0, v13, vcc
	v_add_co_u32_e32 v62, vcc, s5, v12
	s_mov_b32 s5, 0x21000
	s_nop 0
	v_addc_co_u32_e32 v63, vcc, 0, v13, vcc
	global_load_ushort v23, v[22:23], off offset:3072
	s_waitcnt vmcnt(13)
	v_lshlrev_b32_e32 v36, 16, v36
	global_load_ushort v21, v[62:63], off offset:3584
	v_add_co_u32_e32 v62, vcc, s5, v12
	s_mov_b32 s5, 0x22000
	s_nop 0
	v_addc_co_u32_e32 v63, vcc, 0, v13, vcc
	global_load_ushort v22, v[62:63], off
	v_add_co_u32_e32 v62, vcc, s5, v12
	s_mov_b32 s5, 0x23000
	s_nop 0
	v_addc_co_u32_e32 v63, vcc, 0, v13, vcc
	v_add_co_u32_e32 v12, vcc, s5, v12
	global_load_ushort v19, v[62:63], off offset:512
	s_nop 0
	v_addc_co_u32_e32 v13, vcc, 0, v13, vcc
	global_load_ushort v12, v[12:13], off offset:1024
	v_mul_f32_e32 v13, v11, v40
	v_fmac_f32_e32 v13, v10, v47
	v_fmac_f32_e32 v13, v8, v37
	v_lshlrev_b32_e32 v47, 16, v64
	v_fmac_f32_e32 v13, v9, v47
	v_mul_f32_e32 v62, 0xbfb8aa3b, v13
	v_exp_f32_e32 v62, v62
	s_movk_i32 s5, 0x6e
	v_cmp_lt_u32_e32 vcc, s5, v18
	s_waitcnt vmcnt(16)
	v_lshlrev_b32_e32 v35, 16, v35
	v_add_f32_e32 v62, 1.0, v62
	v_rcp_f32_e32 v62, v62
	s_waitcnt vmcnt(14)
	v_lshlrev_b32_e32 v33, 16, v33
	s_waitcnt vmcnt(13)
	v_lshlrev_b32_e32 v32, 16, v32
	s_waitcnt vmcnt(11)
	v_lshlrev_b32_e32 v30, 16, v30
	v_mul_f32_e32 v13, v13, v62
	v_cndmask_b32_e64 v62, 0, 1.0, vcc
	v_mul_f32_e32 v13, v62, v13
	ds_write2_b32 v17, v44, v13 offset1:65
	v_mul_f32_e32 v13, v11, v37
	v_fmac_f32_e32 v13, v10, v40
	v_fmac_f32_e32 v13, v8, v47
	v_lshlrev_b32_e32 v40, 16, v61
	v_fmac_f32_e32 v13, v9, v40
	v_mul_f32_e32 v44, 0xbfb8aa3b, v13
	v_exp_f32_e32 v44, v44
	s_waitcnt vmcnt(10)
	v_lshlrev_b32_e32 v29, 16, v29
	v_add_f32_e32 v44, 1.0, v44
	v_rcp_f32_e32 v44, v44
	s_waitcnt vmcnt(8)
	v_lshlrev_b32_e32 v27, 16, v27
	v_mul_f32_e32 v13, v13, v44
	v_mul_f32_e32 v44, v11, v47
	v_fmac_f32_e32 v44, v10, v37
	v_fmac_f32_e32 v44, v8, v40
	v_lshlrev_b32_e32 v37, 16, v59
	v_fmac_f32_e32 v44, v9, v37
	v_mul_f32_e32 v59, 0xbfb8aa3b, v44
	v_exp_f32_e32 v59, v59
	v_mul_f32_e32 v13, v20, v13
	s_waitcnt vmcnt(7)
	v_lshlrev_b32_e32 v26, 16, v26
	v_add_f32_e32 v59, 1.0, v59
	v_rcp_f32_e32 v59, v59
	s_waitcnt vmcnt(5)
	v_lshlrev_b32_e32 v24, 16, v24
	v_mul_f32_e32 v44, v44, v59
	v_mul_f32_e32 v44, v20, v44
	ds_write2_b32 v17, v13, v44 offset0:130 offset1:195
	v_mul_f32_e32 v13, v11, v40
	v_fmac_f32_e32 v13, v10, v47
	v_fmac_f32_e32 v13, v8, v37
	v_lshlrev_b32_e32 v44, 16, v58
	v_fmac_f32_e32 v13, v9, v44
	v_mul_f32_e32 v47, 0xbfb8aa3b, v13
	v_exp_f32_e32 v47, v47
	s_nop 0
	v_add_f32_e32 v47, 1.0, v47
	v_rcp_f32_e32 v47, v47
	s_nop 0
	v_mul_f32_e32 v13, v13, v47
	v_mul_f32_e32 v47, v11, v37
	v_fmac_f32_e32 v47, v10, v40
	v_fmac_f32_e32 v47, v8, v44
	v_lshlrev_b32_e32 v40, 16, v57
	v_fmac_f32_e32 v47, v9, v40
	v_mul_f32_e32 v57, 0xbfb8aa3b, v47
	v_exp_f32_e32 v57, v57
	v_mul_f32_e32 v13, v20, v13
	v_add_f32_e32 v57, 1.0, v57
	v_rcp_f32_e32 v57, v57
	s_nop 0
	v_mul_f32_e32 v47, v47, v57
	v_mul_f32_e32 v47, v20, v47
	v_add_u32_e32 v57, 0x400, v17
	ds_write2_b32 v57, v13, v47 offset0:4 offset1:69
	v_mul_f32_e32 v13, v11, v44
	v_fmac_f32_e32 v13, v10, v37
	v_fmac_f32_e32 v13, v8, v40
	v_lshlrev_b32_e32 v37, 16, v56
	v_fmac_f32_e32 v13, v9, v37
	v_mul_f32_e32 v47, 0xbfb8aa3b, v13
	v_exp_f32_e32 v47, v47
	s_nop 0
	v_add_f32_e32 v47, 1.0, v47
	v_rcp_f32_e32 v47, v47
	s_nop 0
	v_mul_f32_e32 v13, v13, v47
	v_mul_f32_e32 v47, v11, v40
	v_fmac_f32_e32 v47, v10, v44
	v_fmac_f32_e32 v47, v8, v37
	v_fmac_f32_e32 v47, v9, v43
	v_mul_f32_e32 v44, 0xbfb8aa3b, v47
	v_exp_f32_e32 v44, v44
	v_mul_f32_e32 v13, v20, v13
	v_add_f32_e32 v44, 1.0, v44
	v_rcp_f32_e32 v44, v44
	s_nop 0
	v_mul_f32_e32 v44, v47, v44
	v_mul_f32_e32 v44, v20, v44
	ds_write2_b32 v57, v13, v44 offset0:134 offset1:199
	v_mul_f32_e32 v13, v11, v37
	v_fmac_f32_e32 v13, v10, v40
	v_fmac_f32_e32 v13, v8, v43
	v_fmac_f32_e32 v13, v9, v39
	v_mul_f32_e32 v40, 0xbfb8aa3b, v13
	v_exp_f32_e32 v40, v40
	s_nop 0
	v_add_f32_e32 v40, 1.0, v40
	v_rcp_f32_e32 v40, v40
	s_nop 0
	v_mul_f32_e32 v13, v13, v40
	v_mul_f32_e32 v40, v11, v43
	v_fmac_f32_e32 v40, v10, v37
	v_fmac_f32_e32 v40, v8, v39
	v_lshlrev_b32_e32 v37, 16, v45
	v_fmac_f32_e32 v40, v9, v37
	v_mul_f32_e32 v44, 0xbfb8aa3b, v40
	v_exp_f32_e32 v44, v44
	v_mul_f32_e32 v13, v20, v13
	v_add_f32_e32 v44, 1.0, v44
	v_rcp_f32_e32 v44, v44
	s_nop 0
	v_mul_f32_e32 v40, v40, v44
	v_mul_f32_e32 v40, v20, v40
	v_add_u32_e32 v44, 0x800, v17
	ds_write2_b32 v44, v13, v40 offset0:8 offset1:73
	v_mul_f32_e32 v13, v11, v39
	v_fmac_f32_e32 v13, v10, v43
	v_fmac_f32_e32 v13, v8, v37
	v_lshlrev_b32_e32 v40, 16, v46
	v_fmac_f32_e32 v13, v9, v40
	v_mul_f32_e32 v43, 0xbfb8aa3b, v13
	v_exp_f32_e32 v43, v43
	s_nop 0
	v_add_f32_e32 v43, 1.0, v43
	v_rcp_f32_e32 v43, v43
	s_nop 0
	v_mul_f32_e32 v13, v13, v43
	v_mul_f32_e32 v43, v11, v37
	v_fmac_f32_e32 v43, v10, v39
	v_fmac_f32_e32 v43, v8, v40
	v_lshlrev_b32_e32 v39, 16, v42
	v_fmac_f32_e32 v43, v9, v39
	v_mul_f32_e32 v42, 0xbfb8aa3b, v43
	v_exp_f32_e32 v42, v42
	v_mul_f32_e32 v13, v20, v13
	v_add_f32_e32 v42, 1.0, v42
	v_rcp_f32_e32 v42, v42
	s_nop 0
	v_mul_f32_e32 v42, v43, v42
	v_mul_f32_e32 v42, v20, v42
	ds_write2_b32 v44, v13, v42 offset0:138 offset1:203
	v_mul_f32_e32 v13, v11, v40
	v_fmac_f32_e32 v13, v10, v37
	v_fmac_f32_e32 v13, v8, v39
	v_lshlrev_b32_e32 v37, 16, v41
	v_fmac_f32_e32 v13, v9, v37
	v_mul_f32_e32 v41, 0xbfb8aa3b, v13
	v_exp_f32_e32 v41, v41
	s_nop 0
	v_add_f32_e32 v41, 1.0, v41
	v_rcp_f32_e32 v41, v41
	s_nop 0
	v_mul_f32_e32 v13, v13, v41
	v_mul_f32_e32 v41, v11, v39
	v_fmac_f32_e32 v41, v10, v40
	v_fmac_f32_e32 v41, v8, v37
	v_fmac_f32_e32 v41, v9, v38
	v_mul_f32_e32 v40, 0xbfb8aa3b, v41
	v_exp_f32_e32 v40, v40
	v_mul_f32_e32 v13, v20, v13
	v_add_f32_e32 v40, 1.0, v40
	v_rcp_f32_e32 v40, v40
	s_nop 0
	v_mul_f32_e32 v40, v41, v40
	v_mul_f32_e32 v40, v20, v40
	v_add_u32_e32 v41, 0xc00, v17
	ds_write2_b32 v41, v13, v40 offset0:12 offset1:77
	v_mul_f32_e32 v13, v11, v37
	v_fmac_f32_e32 v13, v10, v39
	v_fmac_f32_e32 v13, v8, v38
	v_fmac_f32_e32 v13, v9, v36
	v_mul_f32_e32 v39, 0xbfb8aa3b, v13
	v_exp_f32_e32 v39, v39
	s_nop 0
	v_add_f32_e32 v39, 1.0, v39
	v_rcp_f32_e32 v39, v39
	s_nop 0
	v_mul_f32_e32 v13, v13, v39
	v_mul_f32_e32 v39, v11, v38
	v_fmac_f32_e32 v39, v10, v37
	v_fmac_f32_e32 v39, v8, v36
	v_fmac_f32_e32 v39, v9, v35
	v_mul_f32_e32 v37, 0xbfb8aa3b, v39
	v_exp_f32_e32 v37, v37
	v_mul_f32_e32 v13, v20, v13
	v_add_f32_e32 v37, 1.0, v37
	v_rcp_f32_e32 v37, v37
	s_nop 0
	v_mul_f32_e32 v37, v39, v37
	v_mul_f32_e32 v20, v20, v37
	ds_write2_b32 v41, v13, v20 offset0:142 offset1:207
	v_mul_f32_e32 v13, v11, v36
	v_fmac_f32_e32 v13, v10, v38
	v_fmac_f32_e32 v13, v8, v35
	v_lshlrev_b32_e32 v20, 16, v34
	v_fmac_f32_e32 v13, v9, v20
	v_mul_f32_e32 v34, 0xbfb8aa3b, v13
	v_exp_f32_e32 v34, v34
	s_nop 0
	v_add_f32_e32 v34, 1.0, v34
	v_rcp_f32_e32 v34, v34
	s_nop 0
	v_mul_f32_e32 v34, v13, v34
	v_or_b32_e32 v13, 16, v18
	v_cmp_lt_u32_e32 vcc, s12, v13
	s_nop 1
	v_cndmask_b32_e64 v13, 0, 1.0, vcc
	v_mul_f32_e32 v18, v13, v34
	v_mul_f32_e32 v34, v11, v35
	v_fmac_f32_e32 v34, v10, v36
	v_fmac_f32_e32 v34, v8, v20
	v_fmac_f32_e32 v34, v9, v33
	v_mul_f32_e32 v36, 0xbfb8aa3b, v34
	v_exp_f32_e32 v36, v36
	s_nop 0
	v_add_f32_e32 v36, 1.0, v36
	v_rcp_f32_e32 v36, v36
	s_nop 0
	v_mul_f32_e32 v34, v34, v36
	v_mul_f32_e32 v34, v13, v34
	v_add_u32_e32 v36, 0x1000, v17
	ds_write2_b32 v36, v18, v34 offset0:16 offset1:81
	v_mul_f32_e32 v18, v11, v20
	v_fmac_f32_e32 v18, v10, v35
	v_fmac_f32_e32 v18, v8, v33
	v_fmac_f32_e32 v18, v9, v32
	v_mul_f32_e32 v34, 0xbfb8aa3b, v18
	v_exp_f32_e32 v34, v34
	s_nop 0
	v_add_f32_e32 v34, 1.0, v34
	v_rcp_f32_e32 v34, v34
	s_nop 0
	v_mul_f32_e32 v18, v18, v34
	v_mul_f32_e32 v34, v11, v33
	v_fmac_f32_e32 v34, v10, v20
	v_fmac_f32_e32 v34, v8, v32
	v_lshlrev_b32_e32 v20, 16, v31
	v_fmac_f32_e32 v34, v9, v20
	v_mul_f32_e32 v31, 0xbfb8aa3b, v34
	v_exp_f32_e32 v31, v31
	v_mul_f32_e32 v18, v13, v18
	v_add_f32_e32 v31, 1.0, v31
	v_rcp_f32_e32 v31, v31
	s_nop 0
	v_mul_f32_e32 v31, v34, v31
	v_mul_f32_e32 v31, v13, v31
	ds_write2_b32 v36, v18, v31 offset0:146 offset1:211
	v_mul_f32_e32 v18, v11, v32
	v_fmac_f32_e32 v18, v10, v33
	v_fmac_f32_e32 v18, v8, v20
	v_fmac_f32_e32 v18, v9, v30
	v_mul_f32_e32 v31, 0xbfb8aa3b, v18
	v_exp_f32_e32 v31, v31
	s_nop 0
	v_add_f32_e32 v31, 1.0, v31
	v_rcp_f32_e32 v31, v31
	s_nop 0
	v_mul_f32_e32 v18, v18, v31
	v_mul_f32_e32 v31, v11, v20
	v_fmac_f32_e32 v31, v10, v32
	v_fmac_f32_e32 v31, v8, v30
	v_fmac_f32_e32 v31, v9, v29
	v_mul_f32_e32 v32, 0xbfb8aa3b, v31
	v_exp_f32_e32 v32, v32
	v_mul_f32_e32 v18, v13, v18
	v_add_f32_e32 v32, 1.0, v32
	v_rcp_f32_e32 v32, v32
	s_nop 0
	v_mul_f32_e32 v31, v31, v32
	v_mul_f32_e32 v31, v13, v31
	v_add_u32_e32 v32, 0x1400, v17
	ds_write2_b32 v32, v18, v31 offset0:20 offset1:85
	v_mul_f32_e32 v18, v11, v30
	v_fmac_f32_e32 v18, v10, v20
	v_fmac_f32_e32 v18, v8, v29
	v_lshlrev_b32_e32 v20, 16, v28
	v_fmac_f32_e32 v18, v9, v20
	v_mul_f32_e32 v28, 0xbfb8aa3b, v18
	v_exp_f32_e32 v28, v28
	s_nop 0
	v_add_f32_e32 v28, 1.0, v28
	v_rcp_f32_e32 v28, v28
	s_nop 0
	v_mul_f32_e32 v18, v18, v28
	v_mul_f32_e32 v28, v11, v29
	v_fmac_f32_e32 v28, v10, v30
	v_fmac_f32_e32 v28, v8, v20
	v_fmac_f32_e32 v28, v9, v27
	v_mul_f32_e32 v30, 0xbfb8aa3b, v28
	v_exp_f32_e32 v30, v30
	v_mul_f32_e32 v18, v13, v18
	v_add_f32_e32 v30, 1.0, v30
	v_rcp_f32_e32 v30, v30
	s_nop 0
	v_mul_f32_e32 v28, v28, v30
	v_mul_f32_e32 v28, v13, v28
	ds_write2_b32 v32, v18, v28 offset0:150 offset1:215
	v_mul_f32_e32 v18, v11, v20
	v_fmac_f32_e32 v18, v10, v29
	v_fmac_f32_e32 v18, v8, v27
	v_fmac_f32_e32 v18, v9, v26
	v_mul_f32_e32 v28, 0xbfb8aa3b, v18
	v_exp_f32_e32 v28, v28
	s_nop 0
	v_add_f32_e32 v28, 1.0, v28
	v_rcp_f32_e32 v28, v28
	s_nop 0
	v_mul_f32_e32 v18, v18, v28
	v_mul_f32_e32 v28, v11, v27
	v_fmac_f32_e32 v28, v10, v20
	v_fmac_f32_e32 v28, v8, v26
	v_lshlrev_b32_e32 v20, 16, v25
	v_fmac_f32_e32 v28, v9, v20
	v_mul_f32_e32 v25, 0xbfb8aa3b, v28
	v_exp_f32_e32 v25, v25
	v_mul_f32_e32 v18, v13, v18
	v_add_f32_e32 v25, 1.0, v25
	v_rcp_f32_e32 v25, v25
	s_nop 0
	v_mul_f32_e32 v25, v28, v25
	v_mul_f32_e32 v25, v13, v25
	v_add_u32_e32 v28, 0x1800, v17
	ds_write2_b32 v28, v18, v25 offset0:24 offset1:89
	v_mul_f32_e32 v18, v11, v26
	v_fmac_f32_e32 v18, v10, v27
	v_fmac_f32_e32 v18, v8, v20
	v_fmac_f32_e32 v18, v9, v24
	v_mul_f32_e32 v25, 0xbfb8aa3b, v18
	v_exp_f32_e32 v25, v25
	s_nop 0
	v_add_f32_e32 v25, 1.0, v25
	v_rcp_f32_e32 v25, v25
	s_nop 0
	v_mul_f32_e32 v18, v18, v25
	v_mul_f32_e32 v25, v11, v20
	v_fmac_f32_e32 v25, v10, v26
	v_fmac_f32_e32 v25, v8, v24
	s_waitcnt vmcnt(4)
	v_lshlrev_b32_e32 v26, 16, v23
	v_fmac_f32_e32 v25, v9, v26
	v_mul_f32_e32 v23, 0xbfb8aa3b, v25
	v_exp_f32_e32 v23, v23
	v_mul_f32_e32 v18, v13, v18
	v_add_f32_e32 v23, 1.0, v23
	v_rcp_f32_e32 v23, v23
	s_nop 0
	v_mul_f32_e32 v23, v25, v23
	v_mul_f32_e32 v23, v13, v23
	ds_write2_b32 v28, v18, v23 offset0:154 offset1:219
	v_mul_f32_e32 v18, v11, v24
	v_fmac_f32_e32 v18, v10, v20
	v_fmac_f32_e32 v18, v8, v26
	s_waitcnt vmcnt(2)
	v_lshlrev_b32_e32 v23, 16, v22
	v_lshlrev_b32_e32 v22, 16, v21
	v_fmac_f32_e32 v18, v9, v22
	v_mul_f32_e32 v21, 0xbfb8aa3b, v18
	v_exp_f32_e32 v21, v21
	v_mul_f32_e32 v20, v11, v26
	v_fmac_f32_e32 v20, v10, v24
	v_fmac_f32_e32 v20, v8, v22
	v_add_f32_e32 v21, 1.0, v21
	v_rcp_f32_e32 v21, v21
	v_fmac_f32_e32 v20, v9, v23
	v_mul_f32_e32 v18, v18, v21
	v_mul_f32_e32 v21, 0xbfb8aa3b, v20
	v_exp_f32_e32 v21, v21
	v_mul_f32_e32 v18, v13, v18
	v_add_f32_e32 v21, 1.0, v21
	v_rcp_f32_e32 v21, v21
	s_nop 0
	v_mul_f32_e32 v20, v20, v21
	v_mul_f32_e32 v20, v13, v20
	v_add_u32_e32 v21, 0x1c00, v17
	ds_write2_b32 v21, v18, v20 offset0:28 offset1:93
	v_mul_f32_e32 v18, v11, v22
	v_fmac_f32_e32 v18, v10, v26
	v_fmac_f32_e32 v18, v8, v23
	v_pk_mul_f32 v[10:11], v[10:11], v[22:23]
	s_waitcnt vmcnt(0)
	v_lshlrev_b32_e32 v21, 16, v12
	v_lshlrev_b32_e32 v20, 16, v19
	v_fmac_f32_e32 v18, v9, v20
	v_pk_mul_f32 v[8:9], v[8:9], v[20:21]
	v_add_f32_e32 v10, v10, v11
	v_mul_f32_e32 v12, 0xbfb8aa3b, v18
	v_add_f32_e32 v8, v10, v8
	v_exp_f32_e32 v12, v12
	v_add_f32_e32 v8, v8, v9
	v_mul_f32_e32 v9, 0xbfb8aa3b, v8
	v_exp_f32_e32 v9, v9
	v_add_f32_e32 v12, 1.0, v12
	v_rcp_f32_e32 v12, v12
	v_add_f32_e32 v9, 1.0, v9
	v_rcp_f32_e32 v9, v9
	v_mul_f32_e32 v12, v18, v12
	v_mul_f32_e32 v12, v13, v12
	ds_write_b32 v17, v12 offset:7800
	v_mul_f32_e32 v8, v8, v9

.LBB0_511:
	s_or_b64 exec, exec, s[6:7]
	v_cmp_lt_i32_e32 vcc, 63, v16
	s_and_saveexec_b64 s[6:7], vcc
	s_xor_b64 s[6:7], exec, s[6:7]
	v_mbcnt_lo_u32_b32 v8, -1, 0
	v_mbcnt_hi_u32_b32 v8, -1, v8
	v_and_b32_e32 v9, 64, v8
	s_or_saveexec_b64 s[6:7], s[6:7]
	v_and_b32_e32 v18, 63, v16
	s_xor_b64 exec, exec, s[6:7]
	s_cbranch_execz .LBB0_517
	v_lshl_add_u32 v8, s4, 6, v16
	s_movk_i32 s4, 0x6f
	v_cmp_lt_i32_e32 vcc, s4, v8
	v_mov_b32_e32 v8, 0
	v_mov_b32_e32 v10, 0
	s_and_saveexec_b64 s[8:9], vcc
	s_cbranch_execz .LBB0_516
	v_ashrrev_i32_e32 v17, 31, v16
	v_lshl_add_u64 v[8:9], s[2:3], 0, v[16:17]
	v_readlane_b32 s2, v254, 44
	v_lshlrev_b64 v[8:9], 5, v[8:9]
	v_readlane_b32 s3, v254, 45
	v_lshl_add_u64 v[8:9], v[54:55], 0, v[8:9]
	s_mov_b32 s5, s3
	s_lshl_b32 s4, s11, 2
	v_lshl_add_u64 v[10:11], v[8:9], 0, s[4:5]
	global_load_dword v8, v[10:11], off
	global_load_dword v65, v[10:11], off offset:16
	s_or_b32 s4, s11, s18
	s_ashr_i32 s5, s4, 31
	s_lshl_b64 s[4:5], s[4:5], 2
	v_lshl_add_u64 v[66:67], v[50:51], 0, s[4:5]
	global_load_dword v68, v[66:67], off
	v_lshl_add_u64 v[66:67], v[6:7], 0, s[4:5]
	global_load_dword v69, v[66:67], off
	v_writelane_b32 v254, s2, 44
	s_waitcnt vmcnt(3)
	v_mul_f32_e32 v8, 0xbfb8aa3b, v8
	v_exp_f32_e32 v8, v8
	v_writelane_b32 v254, s3, 45
	v_add_f32_e32 v8, 1.0, v8
	v_div_scale_f32 v9, s[2:3], v8, v8, 1.0
	v_rcp_f32_e32 v12, v9
	s_or_b32 s2, s11, s18
	s_ashr_i32 s3, s2, 31
	s_lshl_b64 s[2:3], s[2:3], 2
	v_fma_f32 v13, -v9, v12, 1.0
	v_fmac_f32_e32 v12, v13, v12
	v_div_scale_f32 v13, vcc, 1.0, v8, 1.0
	v_mul_f32_e32 v14, v13, v12
	v_fma_f32 v15, -v9, v14, v13
	v_fmac_f32_e32 v14, v15, v12
	v_fma_f32 v9, -v9, v14, v13
	v_div_fmas_f32 v9, v9, v12, v14
	v_div_fixup_f32 v8, v9, v8, 1.0
	s_waitcnt vmcnt(1)
	v_add_f32_e32 v9, v65, v68
	v_max_f32_e32 v11, 0, v9
	v_mul_f32_e64 v9, |v9|, s83
	v_exp_f32_e32 v9, v9
	s_waitcnt vmcnt(0)
	v_mul_f32_e32 v10, 0x3fb8aa3b, v69
	v_add_f32_e32 v9, 1.0, v9
	v_cmp_gt_f32_e32 vcc, s90, v9
	v_exp_f32_e32 v10, v10
	s_nop 0
	v_cndmask_b32_e64 v12, 0, 32, vcc
	v_ldexp_f32 v9, v9, v12
	v_log_f32_e32 v9, v9
	s_nop 0
	v_mul_f32_e32 v12, 0x3f317217, v9
	v_fma_f32 v12, v9, s91, -v12
	v_fmac_f32_e32 v12, 0x3377d1cf, v9
	v_fmac_f32_e32 v12, 0x3f317217, v9
	v_cmp_lt_f32_e64 s[4:5], |v9|, s94
	s_nop 1
	v_cndmask_b32_e64 v9, v9, v12, s[4:5]
	v_cndmask_b32_e32 v12, 0, v196, vcc
	v_sub_f32_e32 v9, v9, v12
	v_add_f32_e32 v9, v11, v9
	v_mul_f32_e64 v10, v9, -v10
